# speedup vs baseline: 1.0248x; 1.0133x over previous
; __device__ __forceinline__ int tid_opaque() { int t = threadIdx.x; asm volatile("" : "+v"(t)); return t; }
; __device__ __forceinline__ void phase_peer_u(const Params& p, int layer, int xs, int wid0, int wstride, char* smraw) {
;   const int tid = tid_opaque(), l = tid & 63, g = l >> 3, j = l & 7;
;   const int wid = wid0 + (tid >> 6);
;   char* xqs = smraw + (tid >> 6) * 256;
;   const int sl = xs >> 1, par = xs & 1;
;   constexpr int TH = T / 2;
;   const unsigned char* Uq = p.Uq + (size_t)(layer * 4 + sl) * NEXP * 128;
;   const unsigned joff = j * 16;
;   u32x4 ni[4];
;   auto load_idx = [&](int tt) {
;     const u32x4* ip = (const u32x4*)((const char*)p.sel_idx + ((unsigned)(2 * tt + par) * 512u + (unsigned)g * 64u));
; #pragma unroll
;     for (int q4 = 0; q4 < 4; ++q4) ni[q4] = ip[q4];
;   };
;   auto issue_rows = [&](int tt, u32x4 (&q)[16], u32x2& xv) {
; #pragma unroll
;     for (int i = 0; i < 16; ++i) q[i] = *(const u32x4*)(Uq + (ni[i >> 2][i & 3] * 128u + joff));
;     xv = *(const u32x2*)((const char*)p.hb + ((unsigned)(2 * tt + par) * 2048u + (unsigned)(sl * 512 + l * 8)));
;   };
;     ...
;   u32x4 qA[16], qB[16]; u32x2 xA = {0u, 0u}, xB = {0u, 0u};
;   int tt = wid;
;   if (tt < TH) { load_idx(tt); issue_rows(tt, qA, xA); if (tt + wstride < TH) load_idx(tt + wstride); }
.LBB0_670:
	s_or_b64 exec, exec, s[0:1]
	v_mov_b32_e32 v16, v189
	s_barrier
	s_ashr_i32 s14, s3, 1
	s_waitcnt vmcnt(5)
	v_ashrrev_i32_e32 v80, 6, v16
	v_add_u32_e32 v169, s92, v80
	s_and_b32 s28, s3, 1
	s_ashr_i32 s15, s14, 31
	s_movk_i32 s3, 0x4020
	s_lshl_b64 s[0:1], s[14:15], 21
	v_cmp_gt_i32_e32 vcc, s3, v169
	s_mul_i32 s29, s33, 3
	s_and_saveexec_b64 s[8:9], vcc
	s_cbranch_execz .LBB0_689
	v_and_b32_e32 v6, 63, v189
	v_lshrrev_b32_e32 v7, 6, v189
	v_lshlrev_b32_e32 v0, 3, v6
	v_and_b32_e32 v1, 7, v6
	v_and_b32_e32 v9, 4, v6
	v_and_b32_e32 v40, 1, v6
	v_and_b32_e32 v41, 2, v6
	v_cmp_ne_u32_e64 s[12:13], 0, v9
	v_cmp_ne_u32_e64 s[72:73], 0, v40
	v_cmp_ne_u32_e64 s[74:75], 0, v41
	v_lshlrev_b32_e32 v1, 4, v1
	v_lshrrev_b32_e32 v8, 3, v6
	v_readfirstlane_b32 s70, v7
	s_lshl_b32 s71, s28, 9
	v_lshl_add_u32 v2, v8, 6, s71
	v_lshlrev_b32_e32 v5, 6, v8
	v_lshlrev_b32_e32 v3, 8, v7
	v_lshl_add_u32 v4, v1, 1, v3
	v_lshl_add_u32 v3, v6, 2, v3
	s_add_u32 s60, s92, s70
	s_movk_i32 s61, 0x4020
	s_cmp_ge_u32 s60, s61
	s_cbranch_scc1 .Lmy_pu0_done
	s_lshl_b32 s70, s14, 21
	s_add_u32 s66, s88, s70
	s_addc_u32 s67, s89, 0
	v_readlane_b32 s64, v254, 4
	v_readlane_b32 s65, v254, 5
	s_lshl_b32 s68, s14, 9
	s_mov_b32 s69, 0x42fe0000
	s_mov_b32 s21, 0xf0f0f0f
	s_mov_b32 s23, 0xf0f0f0f0
	s_lshl_b32 s70, s60, 10
	v_add_u32_e32 v9, s70, v2
	global_load_dwordx4 v[10:13], v9, s[52:53]
	global_load_dwordx4 v[14:17], v9, s[52:53] offset:16
	global_load_dwordx4 v[18:21], v9, s[52:53] offset:32
	global_load_dwordx4 v[22:25], v9, s[52:53] offset:48
	s_waitcnt vmcnt(0)
	v_lshl_add_u32 v6, v10, 7, v1
	global_load_dwordx4 v[106:109], v6, s[66:67]
	v_lshl_add_u32 v7, v11, 7, v1
	global_load_dwordx4 v[110:113], v7, s[66:67]
	v_lshl_add_u32 v6, v12, 7, v1
	global_load_dwordx4 v[114:117], v6, s[66:67]
	v_lshl_add_u32 v7, v13, 7, v1
	global_load_dwordx4 v[118:121], v7, s[66:67]
	v_lshl_add_u32 v6, v14, 7, v1
	global_load_dwordx4 v[122:125], v6, s[66:67]
	v_lshl_add_u32 v7, v15, 7, v1
	global_load_dwordx4 v[126:129], v7, s[66:67]
	v_lshl_add_u32 v6, v16, 7, v1
	global_load_dwordx4 v[130:133], v6, s[66:67]
	v_lshl_add_u32 v7, v17, 7, v1
	global_load_dwordx4 v[134:137], v7, s[66:67]
	v_lshl_add_u32 v6, v18, 7, v1
	global_load_dwordx4 v[138:141], v6, s[66:67]
	v_lshl_add_u32 v7, v19, 7, v1
	global_load_dwordx4 v[142:145], v7, s[66:67]
	v_lshl_add_u32 v6, v20, 7, v1
	global_load_dwordx4 v[146:149], v6, s[66:67]
	v_lshl_add_u32 v7, v21, 7, v1
	global_load_dwordx4 v[150:153], v7, s[66:67]
	v_lshl_add_u32 v6, v22, 7, v1
	global_load_dwordx4 v[154:157], v6, s[66:67]
	v_lshl_add_u32 v7, v23, 7, v1
	global_load_dwordx4 v[158:161], v7, s[66:67]
	v_lshl_add_u32 v6, v24, 7, v1
	global_load_dwordx4 v[162:165], v6, s[66:67]
	v_lshl_add_u32 v7, v25, 7, v1
	global_load_dwordx4 v[166:169], v7, s[66:67]
	s_lshl_b32 s70, s60, 1
	s_add_u32 s70, s70, s28
	s_lshl_b32 s70, s70, 11
	s_add_u32 s70, s70, s68
	v_add_u32_e32 v8, s70, v0
	global_load_dwordx2 v[26:27], v8, s[76:77]
	s_add_u32 s62, s60, s33
	s_cmp_ge_u32 s62, s61
	s_cbranch_scc1 .Lmy_pu0_pro1
	s_lshl_b32 s70, s62, 10
	v_add_u32_e32 v9, s70, v2
	global_load_dwordx4 v[10:13], v9, s[52:53]
	global_load_dwordx4 v[14:17], v9, s[52:53] offset:16
	global_load_dwordx4 v[18:21], v9, s[52:53] offset:32
	global_load_dwordx4 v[22:25], v9, s[52:53] offset:48

; __device__ __forceinline__ float bflo(unsigned u) { return __uint_as_float(u << 16); }
; __device__ __forceinline__ float bfhi(unsigned u) { return __uint_as_float(u & 0xffff0000u); }
; __device__ __forceinline__ void phase_peer_u(const Params& p, int layer, int xs, int wid0, int wstride, char* smraw) {
;     ...
;   auto issue_rows = [&](int tt, u32x4 (&q)[16], u32x2& xv) {
; #pragma unroll
;     for (int i = 0; i < 16; ++i) q[i] = *(const u32x4*)(Uq + (ni[i >> 2][i & 3] * 128u + joff));
;     xv = *(const u32x2*)((const char*)p.hb + ((unsigned)(2 * tt + par) * 2048u + (unsigned)(sl * 512 + l * 8)));
;   };
;     ...
;     int xq[8]; float sx; int sumx = 0;
;     {
;       const float x0 = bflo(xv[0]), x1 = bfhi(xv[0]), x2 = bflo(xv[1]), x3 = bfhi(xv[1]);
;       float mx = fmaxf(fmaxf(fabsf(x0), fabsf(x1)), fmaxf(fabsf(x2), fabsf(x3)));
; #pragma unroll
;       for (int m = 32; m >= 1; m >>= 1) mx = fmaxf(mx, __shfl_xor(mx, m));
;       const float inv = mx > 0.f ? 127.f / mx : 0.f;
;       sx = mx * (1.f / 127.f);
;       const int q0 = __float2int_rn(x0 * inv), q1 = __float2int_rn(x1 * inv), q2 = __float2int_rn(x2 * inv), q3 = __float2int_rn(x3 * inv);
;       asm volatile("" ::: "memory");
;       *(int*)(xqs + l * 4) = (q0 & 0xff) | ((q1 & 0xff) << 8) | ((q2 & 0xff) << 16) | ((q3 & 0xff) << 24);
;       asm volatile("" ::: "memory");
;       __builtin_amdgcn_wave_barrier();
;       asm volatile("" ::: "memory");
;       const u32x4 xa = *(const u32x4*)(xqs + j * 32), xb = *(const u32x4*)(xqs + j * 32 + 16);
;       asm volatile("" ::: "memory");
; #pragma unroll
;       for (int m = 0; m < 4; ++m) { xq[m] = (int)xa[m]; xq[4 + m] = (int)xb[m]; }
; #pragma unroll
;       for (int m = 0; m < 8; ++m) sumx = __builtin_amdgcn_sdot4(xq[m], 0x01010101, sumx, false);
;     }
;     const int corr = 8 * sumx;
;     float pr[16];
; #pragma unroll
;     for (int i = 0; i < 16; ++i) {
;       int a = 0;
; #pragma unroll
;       for (int m = 0; m < 4; ++m) {
;         const unsigned dw = q[i][m];
;         a = __builtin_amdgcn_sdot4((int)(dw & 0x0f0f0f0fu), xq[2 * m], a, false);
;         a = __builtin_amdgcn_sdot4((int)((dw >> 4) & 0x0f0f0f0fu), xq[2 * m + 1], a, false);
;       }
.Lmy_pu0_bodyA:
	s_waitcnt vmcnt(1)
	s_add_u32 s62, s60, s33
	s_cmp_ge_u32 s62, s61
	s_cbranch_scc1 .Lmy_pu0_noissueA
	v_lshl_add_u32 v6, v10, 7, v1
	global_load_dwordx4 v[170:173], v6, s[66:67]
	v_lshl_add_u32 v7, v11, 7, v1
	global_load_dwordx4 v[174:177], v7, s[66:67]
	v_lshl_add_u32 v6, v12, 7, v1
	global_load_dwordx4 v[178:181], v6, s[66:67]
	v_lshl_add_u32 v7, v13, 7, v1
	global_load_dwordx4 v[182:185], v7, s[66:67]
	v_lshl_add_u32 v6, v14, 7, v1
	global_load_dwordx4 v[192:195], v6, s[66:67]
	v_lshl_add_u32 v7, v15, 7, v1
	global_load_dwordx4 v[196:199], v7, s[66:67]
	v_lshl_add_u32 v6, v16, 7, v1
	global_load_dwordx4 v[200:203], v6, s[66:67]
	v_lshl_add_u32 v7, v17, 7, v1
	global_load_dwordx4 v[204:207], v7, s[66:67]
	v_lshl_add_u32 v6, v18, 7, v1
	global_load_dwordx4 v[208:211], v6, s[66:67]
	v_lshl_add_u32 v7, v19, 7, v1
	global_load_dwordx4 v[212:215], v7, s[66:67]
	v_lshl_add_u32 v6, v20, 7, v1
	global_load_dwordx4 v[216:219], v6, s[66:67]
	v_lshl_add_u32 v7, v21, 7, v1
	global_load_dwordx4 v[220:223], v7, s[66:67]
	v_lshl_add_u32 v6, v22, 7, v1
	global_load_dwordx4 v[224:227], v6, s[66:67]
	v_lshl_add_u32 v7, v23, 7, v1
	global_load_dwordx4 v[228:231], v7, s[66:67]
	v_lshl_add_u32 v6, v24, 7, v1
	global_load_dwordx4 v[232:235], v6, s[66:67]
	v_lshl_add_u32 v7, v25, 7, v1
	global_load_dwordx4 v[236:239], v7, s[66:67]
	s_lshl_b32 s70, s62, 1
	s_add_u32 s70, s70, s28
	s_lshl_b32 s70, s70, 11
	s_add_u32 s70, s70, s68
	v_add_u32_e32 v8, s70, v0
	global_load_dwordx2 v[28:29], v8, s[76:77]
	s_add_u32 s63, s62, s33
	s_cmp_ge_u32 s63, s61
	s_cbranch_scc1 .Lmy_pu0_noissueA
	s_lshl_b32 s70, s63, 10
	v_add_u32_e32 v9, s70, v2
	global_load_dwordx4 v[10:13], v9, s[52:53]
	global_load_dwordx4 v[14:17], v9, s[52:53] offset:16
	global_load_dwordx4 v[18:21], v9, s[52:53] offset:32
	global_load_dwordx4 v[22:25], v9, s[52:53] offset:48
.Lmy_pu0_noissueA:
	v_lshlrev_b32_e32 v40, 16, v26
	v_and_b32_e32 v41, 0xffff0000, v26
	v_lshlrev_b32_e32 v42, 16, v27
	v_and_b32_e32 v43, 0xffff0000, v27
	v_max_f32_e64 v44, |v40|, |v41|
	v_max3_f32 v44, |v42|, |v43|, v44
	s_nop 1
	v_max_f32_dpp v44, v44, v44 quad_perm:[1,0,3,2] row_mask:0xf bank_mask:0xf bound_ctrl:1
	s_nop 1
	v_max_f32_dpp v44, v44, v44 quad_perm:[2,3,0,1] row_mask:0xf bank_mask:0xf bound_ctrl:1
	s_nop 1
	v_max_f32_dpp v44, v44, v44 row_half_mirror row_mask:0xf bank_mask:0xf bound_ctrl:1
	s_nop 1
	v_max_f32_dpp v44, v44, v44 row_mirror row_mask:0xf bank_mask:0xf bound_ctrl:1
	s_nop 0
	v_readlane_b32 s6, v44, 0
	v_readlane_b32 s7, v44, 16
	v_readlane_b32 s10, v44, 32
	v_readlane_b32 s11, v44, 48
	s_nop 1
	v_mov_b32_e32 v45, s6
	v_max_f32_e32 v45, s7, v45
	v_max_f32_e32 v45, s10, v45
	v_max_f32_e32 v45, s11, v45
	v_div_scale_f32 v46, s[18:19], v45, v45, s69
	v_rcp_f32_e32 v47, v46
	s_nop 0
	v_fma_f32 v48, -v46, v47, 1.0
	v_fmac_f32_e32 v47, v48, v47
	v_div_scale_f32 v48, vcc, s69, v45, s69
	v_mul_f32_e32 v49, v48, v47
	v_fma_f32 v50, -v46, v49, v48
	v_fmac_f32_e32 v49, v50, v47
	v_fma_f32 v46, -v46, v49, v48
	v_div_fmas_f32 v46, v46, v47, v49
	v_div_fixup_f32 v46, v46, v45, s69
	v_cmp_lt_f32_e32 vcc, 0, v45
	v_mul_f32_e32 v52, 0x3c010204, v45
	v_mov_b32_e32 v84, 0
	v_cndmask_b32_e32 v46, 0, v46, vcc
	v_mul_f32_e32 v40, v46, v40
	v_mul_f32_e32 v41, v46, v41
	v_mul_f32_e32 v42, v46, v42
	v_mul_f32_e32 v43, v46, v43
	v_rndne_f32_e32 v40, v40
	v_rndne_f32_e32 v41, v41
	v_rndne_f32_e32 v42, v42
	v_rndne_f32_e32 v43, v43
	v_cvt_i32_f32_e32 v40, v40
	v_cvt_i32_f32_e32 v41, v41
	v_cvt_i32_f32_e32 v42, v42
	v_cvt_i32_f32_e32 v43, v43
	v_and_b32_e32 v40, 0xff, v40
	v_and_b32_e32 v41, 0xff, v41
	v_and_b32_e32 v42, 0xff, v42
	v_lshl_or_b32 v40, v41, 8, v40
	v_lshl_or_b32 v40, v42, 16, v40
	v_lshl_or_b32 v40, v43, 24, v40
	ds_write_b32 v3, v40
	ds_read_b128 v[32:35], v4
	ds_read_b128 v[36:39], v4 offset:16
	s_waitcnt lgkmcnt(0)
	v_dot4c_i32_i8_e32 v84, 0x1010101, v32
	v_dot4c_i32_i8_e32 v84, 0x1010101, v34
	v_dot4c_i32_i8_e32 v84, 0x1010101, v36
	v_dot4c_i32_i8_e32 v84, 0x1010101, v38
	v_and_b32_e32 v56, s21, v106
	v_and_b32_e32 v57, s23, v106
	v_and_b32_e32 v58, s21, v110
	v_and_b32_e32 v59, s23, v110
	v_and_b32_e32 v60, s21, v114
	v_and_b32_e32 v61, s23, v114
	v_and_b32_e32 v62, s21, v118
	v_and_b32_e32 v63, s23, v118
	v_mul_i32_i24_e32 v85, -8, v84
	v_dot4_i32_i8 v64, v56, v32, v85
	v_dot4_i32_i8 v86, v57, v33, 0
	v_dot4_i32_i8 v65, v58, v32, v85
	v_dot4_i32_i8 v87, v59, v33, 0
	v_dot4_i32_i8 v66, v60, v32, v85
	v_dot4_i32_i8 v88, v61, v33, 0
	v_dot4_i32_i8 v67, v62, v32, v85
	v_dot4_i32_i8 v89, v63, v33, 0
	v_and_b32_e32 v56, s21, v107
	v_and_b32_e32 v57, s23, v107
	v_and_b32_e32 v58, s21, v111
	v_and_b32_e32 v59, s23, v111
	v_and_b32_e32 v60, s21, v115
	v_and_b32_e32 v61, s23, v115
	v_and_b32_e32 v62, s21, v119
	v_and_b32_e32 v63, s23, v119
	v_dot4c_i32_i8_e32 v64, v56, v34
	v_dot4c_i32_i8_e32 v86, v57, v35
	v_dot4c_i32_i8_e32 v65, v58, v34
	v_dot4c_i32_i8_e32 v87, v59, v35
	v_dot4c_i32_i8_e32 v66, v60, v34
	v_dot4c_i32_i8_e32 v88, v61, v35
	v_dot4c_i32_i8_e32 v67, v62, v34
	v_dot4c_i32_i8_e32 v89, v63, v35
	v_and_b32_e32 v56, s21, v108
	v_and_b32_e32 v57, s23, v108
	v_and_b32_e32 v58, s21, v112
	v_and_b32_e32 v59, s23, v112
	v_and_b32_e32 v60, s21, v116
	v_and_b32_e32 v61, s23, v116
	v_and_b32_e32 v62, s21, v120
	v_and_b32_e32 v63, s23, v120
	v_dot4c_i32_i8_e32 v64, v56, v36
	v_dot4c_i32_i8_e32 v86, v57, v37
	v_dot4c_i32_i8_e32 v65, v58, v36
	v_dot4c_i32_i8_e32 v87, v59, v37
	v_dot4c_i32_i8_e32 v66, v60, v36
	v_dot4c_i32_i8_e32 v88, v61, v37
	v_dot4c_i32_i8_e32 v67, v62, v36
	v_dot4c_i32_i8_e32 v89, v63, v37
	v_and_b32_e32 v56, s21, v109
	v_and_b32_e32 v57, s23, v109
	v_and_b32_e32 v58, s21, v113
; __device__ __forceinline__ void phase_peer_u(const Params& p, int layer, int xs, int wid0, int wstride, char* smraw) {
;     ...
;     float pr[16];
; #pragma unroll
;     for (int i = 0; i < 16; ++i) {
;       int a = 0;
; #pragma unroll
;       for (int m = 0; m < 4; ++m) {
;         const unsigned dw = q[i][m];
;         a = __builtin_amdgcn_sdot4((int)(dw & 0x0f0f0f0fu), xq[2 * m], a, false);
;         a = __builtin_amdgcn_sdot4((int)((dw >> 4) & 0x0f0f0f0fu), xq[2 * m + 1], a, false);
;       }
;       a -= corr;
;       a += __builtin_amdgcn_update_dpp(0, a, 0xB1, 0xF, 0xF, true);
;       a += __builtin_amdgcn_update_dpp(0, a, 0x4E, 0xF, 0xF, true);
;       a += __builtin_amdgcn_update_dpp(0, a, 0x141, 0xF, 0xF, true);
;       pr[i] = (float)a * sx;
;     }
	v_and_b32_e32 v59, s23, v113
	v_and_b32_e32 v60, s21, v117
	v_and_b32_e32 v61, s23, v117
	v_and_b32_e32 v62, s21, v121
	v_and_b32_e32 v63, s23, v121
	v_dot4c_i32_i8_e32 v64, v56, v38
	v_dot4c_i32_i8_e32 v86, v57, v39
	v_dot4c_i32_i8_e32 v65, v58, v38
	v_dot4c_i32_i8_e32 v87, v59, v39
	v_dot4c_i32_i8_e32 v66, v60, v38
	v_dot4c_i32_i8_e32 v88, v61, v39
	v_dot4c_i32_i8_e32 v67, v62, v38
	v_dot4c_i32_i8_e32 v89, v63, v39
	v_ashrrev_i32_e32 v86, 4, v86
	v_ashrrev_i32_e32 v87, 4, v87
	v_ashrrev_i32_e32 v88, 4, v88
	v_ashrrev_i32_e32 v89, 4, v89
	v_add_u32_e32 v68, v64, v86
	v_add_u32_e32 v69, v65, v87
	v_add_u32_e32 v70, v66, v88
	v_add_u32_e32 v71, v67, v89
	v_and_b32_e32 v56, s21, v122
	v_and_b32_e32 v57, s23, v122
	v_and_b32_e32 v58, s21, v126
	v_and_b32_e32 v59, s23, v126
	v_and_b32_e32 v60, s21, v130
	v_and_b32_e32 v61, s23, v130
	v_and_b32_e32 v62, s21, v134
	v_and_b32_e32 v63, s23, v134
	v_dot4_i32_i8 v64, v56, v32, v85
	v_dot4_i32_i8 v86, v57, v33, 0
	v_dot4_i32_i8 v65, v58, v32, v85
	v_dot4_i32_i8 v87, v59, v33, 0
	v_dot4_i32_i8 v66, v60, v32, v85
	v_dot4_i32_i8 v88, v61, v33, 0
	v_dot4_i32_i8 v67, v62, v32, v85
	v_dot4_i32_i8 v89, v63, v33, 0
	v_and_b32_e32 v56, s21, v123
	v_and_b32_e32 v57, s23, v123
	v_and_b32_e32 v58, s21, v127
	v_and_b32_e32 v59, s23, v127
	v_and_b32_e32 v60, s21, v131
	v_and_b32_e32 v61, s23, v131
	v_and_b32_e32 v62, s21, v135
	v_and_b32_e32 v63, s23, v135
	v_dot4c_i32_i8_e32 v64, v56, v34
	v_dot4c_i32_i8_e32 v86, v57, v35
	v_dot4c_i32_i8_e32 v65, v58, v34
	v_dot4c_i32_i8_e32 v87, v59, v35
	v_dot4c_i32_i8_e32 v66, v60, v34
	v_dot4c_i32_i8_e32 v88, v61, v35
	v_dot4c_i32_i8_e32 v67, v62, v34
	v_dot4c_i32_i8_e32 v89, v63, v35
	v_and_b32_e32 v56, s21, v124
	v_and_b32_e32 v57, s23, v124
	v_and_b32_e32 v58, s21, v128
	v_and_b32_e32 v59, s23, v128
	v_and_b32_e32 v60, s21, v132
	v_and_b32_e32 v61, s23, v132
	v_and_b32_e32 v62, s21, v136
	v_and_b32_e32 v63, s23, v136
	v_dot4c_i32_i8_e32 v64, v56, v36
	v_dot4c_i32_i8_e32 v86, v57, v37
	v_dot4c_i32_i8_e32 v65, v58, v36
	v_dot4c_i32_i8_e32 v87, v59, v37
	v_dot4c_i32_i8_e32 v66, v60, v36
	v_dot4c_i32_i8_e32 v88, v61, v37
	v_dot4c_i32_i8_e32 v67, v62, v36
	v_dot4c_i32_i8_e32 v89, v63, v37
	v_and_b32_e32 v56, s21, v125
	v_and_b32_e32 v57, s23, v125
	v_and_b32_e32 v58, s21, v129
	v_and_b32_e32 v59, s23, v129
	v_and_b32_e32 v60, s21, v133
	v_and_b32_e32 v61, s23, v133
	v_and_b32_e32 v62, s21, v137
	v_and_b32_e32 v63, s23, v137
	v_dot4c_i32_i8_e32 v64, v56, v38
	v_dot4c_i32_i8_e32 v86, v57, v39
	v_dot4c_i32_i8_e32 v65, v58, v38
	v_dot4c_i32_i8_e32 v87, v59, v39
	v_dot4c_i32_i8_e32 v66, v60, v38
	v_dot4c_i32_i8_e32 v88, v61, v39
	v_dot4c_i32_i8_e32 v67, v62, v38
	v_dot4c_i32_i8_e32 v89, v63, v39
	v_ashrrev_i32_e32 v86, 4, v86
	v_ashrrev_i32_e32 v87, 4, v87
	v_ashrrev_i32_e32 v88, 4, v88
	v_ashrrev_i32_e32 v89, 4, v89
	v_add_u32_e32 v72, v64, v86
	v_add_u32_e32 v73, v65, v87
	v_add_u32_e32 v74, v66, v88
	v_add_u32_e32 v75, v67, v89
	v_and_b32_e32 v56, s21, v138
	v_and_b32_e32 v57, s23, v138
	v_and_b32_e32 v58, s21, v142
	v_and_b32_e32 v59, s23, v142
	v_and_b32_e32 v60, s21, v146
	v_and_b32_e32 v61, s23, v146
	v_and_b32_e32 v62, s21, v150
	v_and_b32_e32 v63, s23, v150
	v_dot4_i32_i8 v64, v56, v32, v85
	v_dot4_i32_i8 v86, v57, v33, 0
	v_dot4_i32_i8 v65, v58, v32, v85
	v_dot4_i32_i8 v87, v59, v33, 0
	v_dot4_i32_i8 v66, v60, v32, v85
	v_dot4_i32_i8 v88, v61, v33, 0
	v_dot4_i32_i8 v67, v62, v32, v85
	v_dot4_i32_i8 v89, v63, v33, 0
	v_and_b32_e32 v56, s21, v139
	v_and_b32_e32 v57, s23, v139
	v_and_b32_e32 v58, s21, v143
	v_and_b32_e32 v59, s23, v143
	v_and_b32_e32 v60, s21, v147
	v_and_b32_e32 v61, s23, v147
	v_and_b32_e32 v62, s21, v151
	v_and_b32_e32 v63, s23, v151
	v_dot4c_i32_i8_e32 v64, v56, v34
	v_dot4c_i32_i8_e32 v86, v57, v35
	v_dot4c_i32_i8_e32 v65, v58, v34
	v_dot4c_i32_i8_e32 v87, v59, v35
	v_dot4c_i32_i8_e32 v66, v60, v34
	v_dot4c_i32_i8_e32 v88, v61, v35
	v_dot4c_i32_i8_e32 v67, v62, v34
	v_dot4c_i32_i8_e32 v89, v63, v35
	v_and_b32_e32 v56, s21, v140
	v_and_b32_e32 v57, s23, v140
	v_and_b32_e32 v58, s21, v144
	v_and_b32_e32 v59, s23, v144
	v_and_b32_e32 v60, s21, v148
	v_and_b32_e32 v61, s23, v148
	v_and_b32_e32 v62, s21, v152
	v_and_b32_e32 v63, s23, v152
	v_dot4c_i32_i8_e32 v64, v56, v36
	v_dot4c_i32_i8_e32 v86, v57, v37
	v_dot4c_i32_i8_e32 v65, v58, v36
	v_dot4c_i32_i8_e32 v87, v59, v37
	v_dot4c_i32_i8_e32 v66, v60, v36
	v_dot4c_i32_i8_e32 v88, v61, v37
	v_dot4c_i32_i8_e32 v67, v62, v36
	v_dot4c_i32_i8_e32 v89, v63, v37
	v_and_b32_e32 v56, s21, v141
	v_and_b32_e32 v57, s23, v141
	v_and_b32_e32 v58, s21, v145
	v_and_b32_e32 v59, s23, v145
	v_and_b32_e32 v60, s21, v149
	v_and_b32_e32 v61, s23, v149
	v_and_b32_e32 v62, s21, v153
	v_and_b32_e32 v63, s23, v153
	v_dot4c_i32_i8_e32 v64, v56, v38
	v_dot4c_i32_i8_e32 v86, v57, v39
	v_dot4c_i32_i8_e32 v65, v58, v38
	v_dot4c_i32_i8_e32 v87, v59, v39
	v_dot4c_i32_i8_e32 v66, v60, v38
	v_dot4c_i32_i8_e32 v88, v61, v39
	v_dot4c_i32_i8_e32 v67, v62, v38
	v_dot4c_i32_i8_e32 v89, v63, v39
	v_ashrrev_i32_e32 v86, 4, v86
	v_ashrrev_i32_e32 v87, 4, v87
	v_ashrrev_i32_e32 v88, 4, v88
	v_ashrrev_i32_e32 v89, 4, v89
	v_add_u32_e32 v76, v64, v86
	v_add_u32_e32 v77, v65, v87
	v_add_u32_e32 v78, v66, v88
	v_add_u32_e32 v79, v67, v89
	v_and_b32_e32 v56, s21, v154
	v_and_b32_e32 v57, s23, v154
	v_and_b32_e32 v58, s21, v158
	v_and_b32_e32 v59, s23, v158
	v_and_b32_e32 v60, s21, v162
	v_and_b32_e32 v61, s23, v162
	v_and_b32_e32 v62, s21, v166
	v_and_b32_e32 v63, s23, v166
	v_dot4_i32_i8 v64, v56, v32, v85
	v_dot4_i32_i8 v86, v57, v33, 0
	v_dot4_i32_i8 v65, v58, v32, v85
	v_dot4_i32_i8 v87, v59, v33, 0
	v_dot4_i32_i8 v66, v60, v32, v85
; __device__ __forceinline__ void phase_peer_u(const Params& p, int layer, int xs, int wid0, int wstride, char* smraw) {
;     ...
;   auto issue_rows = [&](int tt, u32x4 (&q)[16], u32x2& xv) {
; #pragma unroll
;     for (int i = 0; i < 16; ++i) q[i] = *(const u32x4*)(Uq + (ni[i >> 2][i & 3] * 128u + joff));
;     xv = *(const u32x2*)((const char*)p.hb + ((unsigned)(2 * tt + par) * 2048u + (unsigned)(sl * 512 + l * 8)));
;   };
;     ...
;     for (int i = 0; i < 16; ++i) {
;       int a = 0;
; #pragma unroll
;       for (int m = 0; m < 4; ++m) {
;         const unsigned dw = q[i][m];
;         a = __builtin_amdgcn_sdot4((int)(dw & 0x0f0f0f0fu), xq[2 * m], a, false);
;         a = __builtin_amdgcn_sdot4((int)((dw >> 4) & 0x0f0f0f0fu), xq[2 * m + 1], a, false);
;       }
;       a -= corr;
;       a += __builtin_amdgcn_update_dpp(0, a, 0xB1, 0xF, 0xF, true);
;       a += __builtin_amdgcn_update_dpp(0, a, 0x4E, 0xF, 0xF, true);
;       a += __builtin_amdgcn_update_dpp(0, a, 0x141, 0xF, 0xF, true);
;       pr[i] = (float)a * sx;
;     }
;     if (j == 0) {
;       f32x4* dst = (f32x4*)((char*)p.actp + ((unsigned)t * 4096u + (unsigned)(sl * 512 + g * 64)));
; #pragma unroll
;       for (int q4 = 0; q4 < 4; ++q4) dst[q4] = f32x4{pr[q4 * 4], pr[q4 * 4 + 1], pr[q4 * 4 + 2], pr[q4 * 4 + 3]};
;     }
	v_dot4_i32_i8 v88, v61, v33, 0
	v_dot4_i32_i8 v67, v62, v32, v85
	v_dot4_i32_i8 v89, v63, v33, 0
	v_and_b32_e32 v56, s21, v155
	v_and_b32_e32 v57, s23, v155
	v_and_b32_e32 v58, s21, v159
	v_and_b32_e32 v59, s23, v159
	v_and_b32_e32 v60, s21, v163
	v_and_b32_e32 v61, s23, v163
	v_and_b32_e32 v62, s21, v167
	v_and_b32_e32 v63, s23, v167
	v_dot4c_i32_i8_e32 v64, v56, v34
	v_dot4c_i32_i8_e32 v86, v57, v35
	v_dot4c_i32_i8_e32 v65, v58, v34
	v_dot4c_i32_i8_e32 v87, v59, v35
	v_dot4c_i32_i8_e32 v66, v60, v34
	v_dot4c_i32_i8_e32 v88, v61, v35
	v_dot4c_i32_i8_e32 v67, v62, v34
	v_dot4c_i32_i8_e32 v89, v63, v35
	v_and_b32_e32 v56, s21, v156
	v_and_b32_e32 v57, s23, v156
	v_and_b32_e32 v58, s21, v160
	v_and_b32_e32 v59, s23, v160
	v_and_b32_e32 v60, s21, v164
	v_and_b32_e32 v61, s23, v164
	v_and_b32_e32 v62, s21, v168
	v_and_b32_e32 v63, s23, v168
	v_dot4c_i32_i8_e32 v64, v56, v36
	v_dot4c_i32_i8_e32 v86, v57, v37
	v_dot4c_i32_i8_e32 v65, v58, v36
	v_dot4c_i32_i8_e32 v87, v59, v37
	v_dot4c_i32_i8_e32 v66, v60, v36
	v_dot4c_i32_i8_e32 v88, v61, v37
	v_dot4c_i32_i8_e32 v67, v62, v36
	v_dot4c_i32_i8_e32 v89, v63, v37
	v_and_b32_e32 v56, s21, v157
	v_and_b32_e32 v57, s23, v157
	v_and_b32_e32 v58, s21, v161
	v_and_b32_e32 v59, s23, v161
	v_and_b32_e32 v60, s21, v165
	v_and_b32_e32 v61, s23, v165
	v_and_b32_e32 v62, s21, v169
	v_and_b32_e32 v63, s23, v169
	v_dot4c_i32_i8_e32 v64, v56, v38
	v_dot4c_i32_i8_e32 v86, v57, v39
	v_dot4c_i32_i8_e32 v65, v58, v38
	v_dot4c_i32_i8_e32 v87, v59, v39
	v_dot4c_i32_i8_e32 v66, v60, v38
	v_dot4c_i32_i8_e32 v88, v61, v39
	v_dot4c_i32_i8_e32 v67, v62, v38
	v_dot4c_i32_i8_e32 v89, v63, v39
	v_ashrrev_i32_e32 v86, 4, v86
	v_ashrrev_i32_e32 v87, 4, v87
	v_ashrrev_i32_e32 v88, 4, v88
	v_ashrrev_i32_e32 v89, 4, v89
	v_add_u32_e32 v80, v64, v86
	v_add_u32_e32 v81, v65, v87
	v_add_u32_e32 v82, v66, v88
	v_add_u32_e32 v83, v67, v89
	v_cndmask_b32_e64 v94, v76, v68, s[12:13]
	v_cndmask_b32_e64 v95, v77, v69, s[12:13]
	v_cndmask_b32_e64 v96, v78, v70, s[12:13]
	v_cndmask_b32_e64 v97, v79, v71, s[12:13]
	v_cndmask_b32_e64 v98, v80, v72, s[12:13]
	v_cndmask_b32_e64 v99, v81, v73, s[12:13]
	v_cndmask_b32_e64 v100, v82, v74, s[12:13]
	v_cndmask_b32_e64 v101, v83, v75, s[12:13]
	v_cndmask_b32_e64 v86, v68, v76, s[12:13]
	v_cndmask_b32_e64 v87, v69, v77, s[12:13]
	v_cndmask_b32_e64 v88, v70, v78, s[12:13]
	v_cndmask_b32_e64 v89, v71, v79, s[12:13]
	v_cndmask_b32_e64 v90, v72, v80, s[12:13]
	v_cndmask_b32_e64 v91, v73, v81, s[12:13]
	v_cndmask_b32_e64 v92, v74, v82, s[12:13]
	v_cndmask_b32_e64 v93, v75, v83, s[12:13]
	v_add_u32_dpp v68, v94, v86 row_half_mirror row_mask:0xf bank_mask:0xf bound_ctrl:1
	v_add_u32_dpp v69, v95, v87 row_half_mirror row_mask:0xf bank_mask:0xf bound_ctrl:1
	v_add_u32_dpp v70, v96, v88 row_half_mirror row_mask:0xf bank_mask:0xf bound_ctrl:1
	v_add_u32_dpp v71, v97, v89 row_half_mirror row_mask:0xf bank_mask:0xf bound_ctrl:1
	v_add_u32_dpp v72, v98, v90 row_half_mirror row_mask:0xf bank_mask:0xf bound_ctrl:1
	v_add_u32_dpp v73, v99, v91 row_half_mirror row_mask:0xf bank_mask:0xf bound_ctrl:1
	v_add_u32_dpp v74, v100, v92 row_half_mirror row_mask:0xf bank_mask:0xf bound_ctrl:1
	v_add_u32_dpp v75, v101, v93 row_half_mirror row_mask:0xf bank_mask:0xf bound_ctrl:1
	v_cndmask_b32_e64 v94, v70, v68, s[72:73]
	v_cndmask_b32_e64 v95, v71, v69, s[72:73]
	v_cndmask_b32_e64 v96, v74, v72, s[72:73]
	v_cndmask_b32_e64 v97, v75, v73, s[72:73]
	v_cndmask_b32_e64 v86, v68, v70, s[72:73]
	v_cndmask_b32_e64 v87, v69, v71, s[72:73]
	v_cndmask_b32_e64 v88, v72, v74, s[72:73]
	v_cndmask_b32_e64 v89, v73, v75, s[72:73]
	v_add_u32_dpp v68, v94, v86 quad_perm:[1,0,3,2] row_mask:0xf bank_mask:0xf bound_ctrl:1
	v_add_u32_dpp v69, v95, v87 quad_perm:[1,0,3,2] row_mask:0xf bank_mask:0xf bound_ctrl:1
	v_add_u32_dpp v70, v96, v88 quad_perm:[1,0,3,2] row_mask:0xf bank_mask:0xf bound_ctrl:1
	v_add_u32_dpp v71, v97, v89 quad_perm:[1,0,3,2] row_mask:0xf bank_mask:0xf bound_ctrl:1
	v_cndmask_b32_e64 v94, v70, v68, s[74:75]
	v_cndmask_b32_e64 v95, v71, v69, s[74:75]
	v_cndmask_b32_e64 v86, v68, v70, s[74:75]
	v_cndmask_b32_e64 v87, v69, v71, s[74:75]
	v_add_u32_dpp v68, v94, v86 quad_perm:[2,3,0,1] row_mask:0xf bank_mask:0xf bound_ctrl:1
	v_add_u32_dpp v69, v95, v87 quad_perm:[2,3,0,1] row_mask:0xf bank_mask:0xf bound_ctrl:1
	v_cvt_f32_i32_e32 v68, v68
	v_cvt_f32_i32_e32 v69, v69
	s_lshl_b32 s70, s60, 1
	s_add_u32 s70, s70, s28
	s_lshl_b32 s70, s70, 12
	s_add_u32 s70, s70, s68
	v_pk_mul_f32 v[68:69], v[52:53], v[68:69] op_sel_hi:[0,1]
	v_add_u32_e32 v9, s70, v0
	global_store_dwordx2 v9, v[68:69], s[64:65]
	s_mov_b32 s60, s62
	s_cmp_lt_u32 s60, s61
	s_cbranch_scc0 .Lmy_pu0_done
.Lmy_pu0_bodyB:
	s_waitcnt vmcnt(1)
	s_add_u32 s62, s60, s33
	s_cmp_ge_u32 s62, s61
	s_cbranch_scc1 .Lmy_pu0_noissueB
	v_lshl_add_u32 v6, v10, 7, v1
	global_load_dwordx4 v[106:109], v6, s[66:67]
	v_lshl_add_u32 v7, v11, 7, v1
	global_load_dwordx4 v[110:113], v7, s[66:67]
	v_lshl_add_u32 v6, v12, 7, v1
	global_load_dwordx4 v[114:117], v6, s[66:67]
	v_lshl_add_u32 v7, v13, 7, v1
	global_load_dwordx4 v[118:121], v7, s[66:67]
	v_lshl_add_u32 v6, v14, 7, v1
	global_load_dwordx4 v[122:125], v6, s[66:67]
	v_lshl_add_u32 v7, v15, 7, v1
	global_load_dwordx4 v[126:129], v7, s[66:67]
	v_lshl_add_u32 v6, v16, 7, v1
	global_load_dwordx4 v[130:133], v6, s[66:67]
	v_lshl_add_u32 v7, v17, 7, v1
	global_load_dwordx4 v[134:137], v7, s[66:67]
	v_lshl_add_u32 v6, v18, 7, v1
	global_load_dwordx4 v[138:141], v6, s[66:67]
	v_lshl_add_u32 v7, v19, 7, v1
	global_load_dwordx4 v[142:145], v7, s[66:67]
	v_lshl_add_u32 v6, v20, 7, v1
	global_load_dwordx4 v[146:149], v6, s[66:67]
	v_lshl_add_u32 v7, v21, 7, v1
	global_load_dwordx4 v[150:153], v7, s[66:67]
	v_lshl_add_u32 v6, v22, 7, v1
	global_load_dwordx4 v[154:157], v6, s[66:67]
	v_lshl_add_u32 v7, v23, 7, v1
	global_load_dwordx4 v[158:161], v7, s[66:67]
	v_lshl_add_u32 v6, v24, 7, v1
	global_load_dwordx4 v[162:165], v6, s[66:67]
	v_lshl_add_u32 v7, v25, 7, v1
	global_load_dwordx4 v[166:169], v7, s[66:67]
	s_lshl_b32 s70, s62, 1
	s_add_u32 s70, s70, s28
	s_lshl_b32 s70, s70, 11
	s_add_u32 s70, s70, s68
	v_add_u32_e32 v8, s70, v0
	global_load_dwordx2 v[26:27], v8, s[76:77]
	s_add_u32 s63, s62, s33
	s_cmp_ge_u32 s63, s61
	s_cbranch_scc1 .Lmy_pu0_noissueB
	s_lshl_b32 s70, s63, 10
	v_add_u32_e32 v9, s70, v2
	global_load_dwordx4 v[10:13], v9, s[52:53]
	global_load_dwordx4 v[14:17], v9, s[52:53] offset:16
	global_load_dwordx4 v[18:21], v9, s[52:53] offset:32
	global_load_dwordx4 v[22:25], v9, s[52:53] offset:48
; __device__ __forceinline__ float bflo(unsigned u) { return __uint_as_float(u << 16); }
; __device__ __forceinline__ float bfhi(unsigned u) { return __uint_as_float(u & 0xffff0000u); }
; __device__ __forceinline__ void phase_peer_u(const Params& p, int layer, int xs, int wid0, int wstride, char* smraw) {
;     ...
;       const float x0 = bflo(xv[0]), x1 = bfhi(xv[0]), x2 = bflo(xv[1]), x3 = bfhi(xv[1]);
;       float mx = fmaxf(fmaxf(fabsf(x0), fabsf(x1)), fmaxf(fabsf(x2), fabsf(x3)));
; #pragma unroll
;       for (int m = 32; m >= 1; m >>= 1) mx = fmaxf(mx, __shfl_xor(mx, m));
;       const float inv = mx > 0.f ? 127.f / mx : 0.f;
;       sx = mx * (1.f / 127.f);
;       const int q0 = __float2int_rn(x0 * inv), q1 = __float2int_rn(x1 * inv), q2 = __float2int_rn(x2 * inv), q3 = __float2int_rn(x3 * inv);
;       asm volatile("" ::: "memory");
;       *(int*)(xqs + l * 4) = (q0 & 0xff) | ((q1 & 0xff) << 8) | ((q2 & 0xff) << 16) | ((q3 & 0xff) << 24);
;       asm volatile("" ::: "memory");
;       __builtin_amdgcn_wave_barrier();
;       asm volatile("" ::: "memory");
;       const u32x4 xa = *(const u32x4*)(xqs + j * 32), xb = *(const u32x4*)(xqs + j * 32 + 16);
;       asm volatile("" ::: "memory");
; #pragma unroll
;       for (int m = 0; m < 4; ++m) { xq[m] = (int)xa[m]; xq[4 + m] = (int)xb[m]; }
; #pragma unroll
;       for (int m = 0; m < 8; ++m) sumx = __builtin_amdgcn_sdot4(xq[m], 0x01010101, sumx, false);
;     }
;     const int corr = 8 * sumx;
;     float pr[16];
; #pragma unroll
;     for (int i = 0; i < 16; ++i) {
;       int a = 0;
; #pragma unroll
;       for (int m = 0; m < 4; ++m) {
;         const unsigned dw = q[i][m];
;         a = __builtin_amdgcn_sdot4((int)(dw & 0x0f0f0f0fu), xq[2 * m], a, false);
;         a = __builtin_amdgcn_sdot4((int)((dw >> 4) & 0x0f0f0f0fu), xq[2 * m + 1], a, false);
;       }
;       a -= corr;
.Lmy_pu0_noissueB:
	v_lshlrev_b32_e32 v40, 16, v28
	v_and_b32_e32 v41, 0xffff0000, v28
	v_lshlrev_b32_e32 v42, 16, v29
	v_and_b32_e32 v43, 0xffff0000, v29
	v_max_f32_e64 v44, |v40|, |v41|
	v_max3_f32 v44, |v42|, |v43|, v44
	s_nop 1
	v_max_f32_dpp v44, v44, v44 quad_perm:[1,0,3,2] row_mask:0xf bank_mask:0xf bound_ctrl:1
	s_nop 1
	v_max_f32_dpp v44, v44, v44 quad_perm:[2,3,0,1] row_mask:0xf bank_mask:0xf bound_ctrl:1
	s_nop 1
	v_max_f32_dpp v44, v44, v44 row_half_mirror row_mask:0xf bank_mask:0xf bound_ctrl:1
	s_nop 1
	v_max_f32_dpp v44, v44, v44 row_mirror row_mask:0xf bank_mask:0xf bound_ctrl:1
	s_nop 0
	v_readlane_b32 s6, v44, 0
	v_readlane_b32 s7, v44, 16
	v_readlane_b32 s10, v44, 32
	v_readlane_b32 s11, v44, 48
	s_nop 1
	v_mov_b32_e32 v45, s6
	v_max_f32_e32 v45, s7, v45
	v_max_f32_e32 v45, s10, v45
	v_max_f32_e32 v45, s11, v45
	v_div_scale_f32 v46, s[18:19], v45, v45, s69
	v_rcp_f32_e32 v47, v46
	s_nop 0
	v_fma_f32 v48, -v46, v47, 1.0
	v_fmac_f32_e32 v47, v48, v47
	v_div_scale_f32 v48, vcc, s69, v45, s69
	v_mul_f32_e32 v49, v48, v47
	v_fma_f32 v50, -v46, v49, v48
	v_fmac_f32_e32 v49, v50, v47
	v_fma_f32 v46, -v46, v49, v48
	v_div_fmas_f32 v46, v46, v47, v49
	v_div_fixup_f32 v46, v46, v45, s69
	v_cmp_lt_f32_e32 vcc, 0, v45
	v_mul_f32_e32 v52, 0x3c010204, v45
	v_mov_b32_e32 v84, 0
	v_cndmask_b32_e32 v46, 0, v46, vcc
	v_mul_f32_e32 v40, v46, v40
	v_mul_f32_e32 v41, v46, v41
	v_mul_f32_e32 v42, v46, v42
	v_mul_f32_e32 v43, v46, v43
	v_rndne_f32_e32 v40, v40
	v_rndne_f32_e32 v41, v41
	v_rndne_f32_e32 v42, v42
	v_rndne_f32_e32 v43, v43
	v_cvt_i32_f32_e32 v40, v40
	v_cvt_i32_f32_e32 v41, v41
	v_cvt_i32_f32_e32 v42, v42
	v_cvt_i32_f32_e32 v43, v43
	v_and_b32_e32 v40, 0xff, v40
	v_and_b32_e32 v41, 0xff, v41
	v_and_b32_e32 v42, 0xff, v42
	v_lshl_or_b32 v40, v41, 8, v40
	v_lshl_or_b32 v40, v42, 16, v40
	v_lshl_or_b32 v40, v43, 24, v40
	ds_write_b32 v3, v40
	ds_read_b128 v[32:35], v4
	ds_read_b128 v[36:39], v4 offset:16
	s_waitcnt lgkmcnt(0)
	v_dot4c_i32_i8_e32 v84, 0x1010101, v32
	v_dot4c_i32_i8_e32 v84, 0x1010101, v34
	v_dot4c_i32_i8_e32 v84, 0x1010101, v36
	v_dot4c_i32_i8_e32 v84, 0x1010101, v38
	v_and_b32_e32 v56, s21, v170
	v_and_b32_e32 v57, s23, v170
	v_and_b32_e32 v58, s21, v174
	v_and_b32_e32 v59, s23, v174
	v_and_b32_e32 v60, s21, v178
	v_and_b32_e32 v61, s23, v178
	v_and_b32_e32 v62, s21, v182
	v_and_b32_e32 v63, s23, v182
	v_mul_i32_i24_e32 v85, -8, v84
	v_dot4_i32_i8 v64, v56, v32, v85
	v_dot4_i32_i8 v86, v57, v33, 0
	v_dot4_i32_i8 v65, v58, v32, v85
	v_dot4_i32_i8 v87, v59, v33, 0
	v_dot4_i32_i8 v66, v60, v32, v85
	v_dot4_i32_i8 v88, v61, v33, 0
	v_dot4_i32_i8 v67, v62, v32, v85
	v_dot4_i32_i8 v89, v63, v33, 0
	v_and_b32_e32 v56, s21, v171
	v_and_b32_e32 v57, s23, v171
	v_and_b32_e32 v58, s21, v175
	v_and_b32_e32 v59, s23, v175
	v_and_b32_e32 v60, s21, v179
	v_and_b32_e32 v61, s23, v179
	v_and_b32_e32 v62, s21, v183
	v_and_b32_e32 v63, s23, v183
	v_dot4c_i32_i8_e32 v64, v56, v34
	v_dot4c_i32_i8_e32 v86, v57, v35
	v_dot4c_i32_i8_e32 v65, v58, v34
	v_dot4c_i32_i8_e32 v87, v59, v35
	v_dot4c_i32_i8_e32 v66, v60, v34
	v_dot4c_i32_i8_e32 v88, v61, v35
	v_dot4c_i32_i8_e32 v67, v62, v34
	v_dot4c_i32_i8_e32 v89, v63, v35
	v_and_b32_e32 v56, s21, v172
	v_and_b32_e32 v57, s23, v172
	v_and_b32_e32 v58, s21, v176
	v_and_b32_e32 v59, s23, v176
	v_and_b32_e32 v60, s21, v180
	v_and_b32_e32 v61, s23, v180
	v_and_b32_e32 v62, s21, v184
	v_and_b32_e32 v63, s23, v184
	v_dot4c_i32_i8_e32 v64, v56, v36
	v_dot4c_i32_i8_e32 v86, v57, v37
	v_dot4c_i32_i8_e32 v65, v58, v36
	v_dot4c_i32_i8_e32 v87, v59, v37
	v_dot4c_i32_i8_e32 v66, v60, v36
	v_dot4c_i32_i8_e32 v88, v61, v37
	v_dot4c_i32_i8_e32 v67, v62, v36
	v_dot4c_i32_i8_e32 v89, v63, v37
	v_and_b32_e32 v56, s21, v173
	v_and_b32_e32 v57, s23, v173
	v_and_b32_e32 v58, s21, v177
	v_and_b32_e32 v59, s23, v177
	v_and_b32_e32 v60, s21, v181
	v_and_b32_e32 v61, s23, v181
	v_and_b32_e32 v62, s21, v185
	v_and_b32_e32 v63, s23, v185
	v_dot4c_i32_i8_e32 v64, v56, v38
	v_dot4c_i32_i8_e32 v86, v57, v39
	v_dot4c_i32_i8_e32 v65, v58, v38
	v_dot4c_i32_i8_e32 v87, v59, v39
	v_dot4c_i32_i8_e32 v66, v60, v38
	v_dot4c_i32_i8_e32 v88, v61, v39
	v_dot4c_i32_i8_e32 v67, v62, v38
	v_dot4c_i32_i8_e32 v89, v63, v39
	v_ashrrev_i32_e32 v86, 4, v86
	v_ashrrev_i32_e32 v87, 4, v87
	v_ashrrev_i32_e32 v88, 4, v88
	v_ashrrev_i32_e32 v89, 4, v89
	v_add_u32_e32 v68, v64, v86
	v_add_u32_e32 v69, v65, v87
	v_add_u32_e32 v70, v66, v88
	v_add_u32_e32 v71, v67, v89
	v_and_b32_e32 v56, s21, v192
	v_and_b32_e32 v57, s23, v192
	v_and_b32_e32 v58, s21, v196
	v_and_b32_e32 v59, s23, v196
	v_and_b32_e32 v60, s21, v200
	v_and_b32_e32 v61, s23, v200
	v_and_b32_e32 v62, s21, v204
	v_and_b32_e32 v63, s23, v204
	v_dot4_i32_i8 v64, v56, v32, v85
	v_dot4_i32_i8 v86, v57, v33, 0
	v_dot4_i32_i8 v65, v58, v32, v85
	v_dot4_i32_i8 v87, v59, v33, 0
	v_dot4_i32_i8 v66, v60, v32, v85
	v_dot4_i32_i8 v88, v61, v33, 0
	v_dot4_i32_i8 v67, v62, v32, v85
	v_dot4_i32_i8 v89, v63, v33, 0
	v_and_b32_e32 v56, s21, v193
	v_and_b32_e32 v57, s23, v193
	v_and_b32_e32 v58, s21, v197
	v_and_b32_e32 v59, s23, v197
	v_and_b32_e32 v60, s21, v201
	v_and_b32_e32 v61, s23, v201
	v_and_b32_e32 v62, s21, v205
	v_and_b32_e32 v63, s23, v205
	v_dot4c_i32_i8_e32 v64, v56, v34
	v_dot4c_i32_i8_e32 v86, v57, v35
	v_dot4c_i32_i8_e32 v65, v58, v34
	v_dot4c_i32_i8_e32 v87, v59, v35
	v_dot4c_i32_i8_e32 v66, v60, v34
	v_dot4c_i32_i8_e32 v88, v61, v35
	v_dot4c_i32_i8_e32 v67, v62, v34
	v_dot4c_i32_i8_e32 v89, v63, v35
	v_and_b32_e32 v56, s21, v194
	v_and_b32_e32 v57, s23, v194
	v_and_b32_e32 v58, s21, v198
	v_and_b32_e32 v59, s23, v198
	v_and_b32_e32 v60, s21, v202
	v_and_b32_e32 v61, s23, v202
; __device__ __forceinline__ void phase_peer_u(const Params& p, int layer, int xs, int wid0, int wstride, char* smraw) {
;     ...
;     for (int i = 0; i < 16; ++i) {
;       int a = 0;
; #pragma unroll
;       for (int m = 0; m < 4; ++m) {
;         const unsigned dw = q[i][m];
;         a = __builtin_amdgcn_sdot4((int)(dw & 0x0f0f0f0fu), xq[2 * m], a, false);
;         a = __builtin_amdgcn_sdot4((int)((dw >> 4) & 0x0f0f0f0fu), xq[2 * m + 1], a, false);
;       }
;       a -= corr;
	v_and_b32_e32 v62, s21, v206
	v_and_b32_e32 v63, s23, v206
	v_dot4c_i32_i8_e32 v64, v56, v36
	v_dot4c_i32_i8_e32 v86, v57, v37
	v_dot4c_i32_i8_e32 v65, v58, v36
	v_dot4c_i32_i8_e32 v87, v59, v37
	v_dot4c_i32_i8_e32 v66, v60, v36
	v_dot4c_i32_i8_e32 v88, v61, v37
	v_dot4c_i32_i8_e32 v67, v62, v36
	v_dot4c_i32_i8_e32 v89, v63, v37
	v_and_b32_e32 v56, s21, v195
	v_and_b32_e32 v57, s23, v195
	v_and_b32_e32 v58, s21, v199
	v_and_b32_e32 v59, s23, v199
	v_and_b32_e32 v60, s21, v203
	v_and_b32_e32 v61, s23, v203
	v_and_b32_e32 v62, s21, v207
	v_and_b32_e32 v63, s23, v207
	v_dot4c_i32_i8_e32 v64, v56, v38
	v_dot4c_i32_i8_e32 v86, v57, v39
	v_dot4c_i32_i8_e32 v65, v58, v38
	v_dot4c_i32_i8_e32 v87, v59, v39
	v_dot4c_i32_i8_e32 v66, v60, v38
	v_dot4c_i32_i8_e32 v88, v61, v39
	v_dot4c_i32_i8_e32 v67, v62, v38
	v_dot4c_i32_i8_e32 v89, v63, v39
	v_ashrrev_i32_e32 v86, 4, v86
	v_ashrrev_i32_e32 v87, 4, v87
	v_ashrrev_i32_e32 v88, 4, v88
	v_ashrrev_i32_e32 v89, 4, v89
	v_add_u32_e32 v72, v64, v86
	v_add_u32_e32 v73, v65, v87
	v_add_u32_e32 v74, v66, v88
	v_add_u32_e32 v75, v67, v89
	v_and_b32_e32 v56, s21, v208
	v_and_b32_e32 v57, s23, v208
	v_and_b32_e32 v58, s21, v212
	v_and_b32_e32 v59, s23, v212
	v_and_b32_e32 v60, s21, v216
	v_and_b32_e32 v61, s23, v216
	v_and_b32_e32 v62, s21, v220
	v_and_b32_e32 v63, s23, v220
	v_dot4_i32_i8 v64, v56, v32, v85
	v_dot4_i32_i8 v86, v57, v33, 0
	v_dot4_i32_i8 v65, v58, v32, v85
	v_dot4_i32_i8 v87, v59, v33, 0
	v_dot4_i32_i8 v66, v60, v32, v85
	v_dot4_i32_i8 v88, v61, v33, 0
	v_dot4_i32_i8 v67, v62, v32, v85
	v_dot4_i32_i8 v89, v63, v33, 0
	v_and_b32_e32 v56, s21, v209
	v_and_b32_e32 v57, s23, v209
	v_and_b32_e32 v58, s21, v213
	v_and_b32_e32 v59, s23, v213
	v_and_b32_e32 v60, s21, v217
	v_and_b32_e32 v61, s23, v217
	v_and_b32_e32 v62, s21, v221
	v_and_b32_e32 v63, s23, v221
	v_dot4c_i32_i8_e32 v64, v56, v34
	v_dot4c_i32_i8_e32 v86, v57, v35
	v_dot4c_i32_i8_e32 v65, v58, v34
	v_dot4c_i32_i8_e32 v87, v59, v35
	v_dot4c_i32_i8_e32 v66, v60, v34
	v_dot4c_i32_i8_e32 v88, v61, v35
	v_dot4c_i32_i8_e32 v67, v62, v34
	v_dot4c_i32_i8_e32 v89, v63, v35
	v_and_b32_e32 v56, s21, v210
	v_and_b32_e32 v57, s23, v210
	v_and_b32_e32 v58, s21, v214
	v_and_b32_e32 v59, s23, v214
	v_and_b32_e32 v60, s21, v218
	v_and_b32_e32 v61, s23, v218
	v_and_b32_e32 v62, s21, v222
	v_and_b32_e32 v63, s23, v222
	v_dot4c_i32_i8_e32 v64, v56, v36
	v_dot4c_i32_i8_e32 v86, v57, v37
	v_dot4c_i32_i8_e32 v65, v58, v36
	v_dot4c_i32_i8_e32 v87, v59, v37
	v_dot4c_i32_i8_e32 v66, v60, v36
	v_dot4c_i32_i8_e32 v88, v61, v37
	v_dot4c_i32_i8_e32 v67, v62, v36
	v_dot4c_i32_i8_e32 v89, v63, v37
	v_and_b32_e32 v56, s21, v211
	v_and_b32_e32 v57, s23, v211
	v_and_b32_e32 v58, s21, v215
	v_and_b32_e32 v59, s23, v215
	v_and_b32_e32 v60, s21, v219
	v_and_b32_e32 v61, s23, v219
	v_and_b32_e32 v62, s21, v223
	v_and_b32_e32 v63, s23, v223
	v_dot4c_i32_i8_e32 v64, v56, v38
	v_dot4c_i32_i8_e32 v86, v57, v39
	v_dot4c_i32_i8_e32 v65, v58, v38
	v_dot4c_i32_i8_e32 v87, v59, v39
	v_dot4c_i32_i8_e32 v66, v60, v38
	v_dot4c_i32_i8_e32 v88, v61, v39
	v_dot4c_i32_i8_e32 v67, v62, v38
	v_dot4c_i32_i8_e32 v89, v63, v39
	v_ashrrev_i32_e32 v86, 4, v86
	v_ashrrev_i32_e32 v87, 4, v87
	v_ashrrev_i32_e32 v88, 4, v88
	v_ashrrev_i32_e32 v89, 4, v89
	v_add_u32_e32 v76, v64, v86
	v_add_u32_e32 v77, v65, v87
	v_add_u32_e32 v78, v66, v88
	v_add_u32_e32 v79, v67, v89
	v_and_b32_e32 v56, s21, v224
	v_and_b32_e32 v57, s23, v224
	v_and_b32_e32 v58, s21, v228
	v_and_b32_e32 v59, s23, v228
	v_and_b32_e32 v60, s21, v232
	v_and_b32_e32 v61, s23, v232
	v_and_b32_e32 v62, s21, v236
	v_and_b32_e32 v63, s23, v236
	v_dot4_i32_i8 v64, v56, v32, v85
	v_dot4_i32_i8 v86, v57, v33, 0
	v_dot4_i32_i8 v65, v58, v32, v85
	v_dot4_i32_i8 v87, v59, v33, 0
	v_dot4_i32_i8 v66, v60, v32, v85
	v_dot4_i32_i8 v88, v61, v33, 0
	v_dot4_i32_i8 v67, v62, v32, v85
	v_dot4_i32_i8 v89, v63, v33, 0
	v_and_b32_e32 v56, s21, v225
	v_and_b32_e32 v57, s23, v225
	v_and_b32_e32 v58, s21, v229
	v_and_b32_e32 v59, s23, v229
	v_and_b32_e32 v60, s21, v233
	v_and_b32_e32 v61, s23, v233
	v_and_b32_e32 v62, s21, v237
	v_and_b32_e32 v63, s23, v237
	v_dot4c_i32_i8_e32 v64, v56, v34
	v_dot4c_i32_i8_e32 v86, v57, v35
	v_dot4c_i32_i8_e32 v65, v58, v34
; __device__ __forceinline__ void phase_peer_u(const Params& p, int layer, int xs, int wid0, int wstride, char* smraw) {
;     ...
;     for (int i = 0; i < 16; ++i) {
;       int a = 0;
; #pragma unroll
;       for (int m = 0; m < 4; ++m) {
;         const unsigned dw = q[i][m];
;         a = __builtin_amdgcn_sdot4((int)(dw & 0x0f0f0f0fu), xq[2 * m], a, false);
;         a = __builtin_amdgcn_sdot4((int)((dw >> 4) & 0x0f0f0f0fu), xq[2 * m + 1], a, false);
;       }
;       a -= corr;
;       a += __builtin_amdgcn_update_dpp(0, a, 0xB1, 0xF, 0xF, true);
;       a += __builtin_amdgcn_update_dpp(0, a, 0x4E, 0xF, 0xF, true);
;       a += __builtin_amdgcn_update_dpp(0, a, 0x141, 0xF, 0xF, true);
;       pr[i] = (float)a * sx;
;     }
;     if (j == 0) {
;       f32x4* dst = (f32x4*)((char*)p.actp + ((unsigned)t * 4096u + (unsigned)(sl * 512 + g * 64)));
; #pragma unroll
;       for (int q4 = 0; q4 < 4; ++q4) dst[q4] = f32x4{pr[q4 * 4], pr[q4 * 4 + 1], pr[q4 * 4 + 2], pr[q4 * 4 + 3]};
;     }
	v_dot4c_i32_i8_e32 v87, v59, v35
	v_dot4c_i32_i8_e32 v66, v60, v34
	v_dot4c_i32_i8_e32 v88, v61, v35
	v_dot4c_i32_i8_e32 v67, v62, v34
	v_dot4c_i32_i8_e32 v89, v63, v35
	v_and_b32_e32 v56, s21, v226
	v_and_b32_e32 v57, s23, v226
	v_and_b32_e32 v58, s21, v230
	v_and_b32_e32 v59, s23, v230
	v_and_b32_e32 v60, s21, v234
	v_and_b32_e32 v61, s23, v234
	v_and_b32_e32 v62, s21, v238
	v_and_b32_e32 v63, s23, v238
	v_dot4c_i32_i8_e32 v64, v56, v36
	v_dot4c_i32_i8_e32 v86, v57, v37
	v_dot4c_i32_i8_e32 v65, v58, v36
	v_dot4c_i32_i8_e32 v87, v59, v37
	v_dot4c_i32_i8_e32 v66, v60, v36
	v_dot4c_i32_i8_e32 v88, v61, v37
	v_dot4c_i32_i8_e32 v67, v62, v36
	v_dot4c_i32_i8_e32 v89, v63, v37
	v_and_b32_e32 v56, s21, v227
	v_and_b32_e32 v57, s23, v227
	v_and_b32_e32 v58, s21, v231
	v_and_b32_e32 v59, s23, v231
	v_and_b32_e32 v60, s21, v235
	v_and_b32_e32 v61, s23, v235
	v_and_b32_e32 v62, s21, v239
	v_and_b32_e32 v63, s23, v239
	v_dot4c_i32_i8_e32 v64, v56, v38
	v_dot4c_i32_i8_e32 v86, v57, v39
	v_dot4c_i32_i8_e32 v65, v58, v38
	v_dot4c_i32_i8_e32 v87, v59, v39
	v_dot4c_i32_i8_e32 v66, v60, v38
	v_dot4c_i32_i8_e32 v88, v61, v39
	v_dot4c_i32_i8_e32 v67, v62, v38
	v_dot4c_i32_i8_e32 v89, v63, v39
	v_ashrrev_i32_e32 v86, 4, v86
	v_ashrrev_i32_e32 v87, 4, v87
	v_ashrrev_i32_e32 v88, 4, v88
	v_ashrrev_i32_e32 v89, 4, v89
	v_add_u32_e32 v80, v64, v86
	v_add_u32_e32 v81, v65, v87
	v_add_u32_e32 v82, v66, v88
	v_add_u32_e32 v83, v67, v89
	v_cndmask_b32_e64 v94, v76, v68, s[12:13]
	v_cndmask_b32_e64 v95, v77, v69, s[12:13]
	v_cndmask_b32_e64 v96, v78, v70, s[12:13]
	v_cndmask_b32_e64 v97, v79, v71, s[12:13]
	v_cndmask_b32_e64 v98, v80, v72, s[12:13]
	v_cndmask_b32_e64 v99, v81, v73, s[12:13]
	v_cndmask_b32_e64 v100, v82, v74, s[12:13]
	v_cndmask_b32_e64 v101, v83, v75, s[12:13]
	v_cndmask_b32_e64 v86, v68, v76, s[12:13]
	v_cndmask_b32_e64 v87, v69, v77, s[12:13]
	v_cndmask_b32_e64 v88, v70, v78, s[12:13]
	v_cndmask_b32_e64 v89, v71, v79, s[12:13]
	v_cndmask_b32_e64 v90, v72, v80, s[12:13]
	v_cndmask_b32_e64 v91, v73, v81, s[12:13]
	v_cndmask_b32_e64 v92, v74, v82, s[12:13]
	v_cndmask_b32_e64 v93, v75, v83, s[12:13]
	v_add_u32_dpp v68, v94, v86 row_half_mirror row_mask:0xf bank_mask:0xf bound_ctrl:1
	v_add_u32_dpp v69, v95, v87 row_half_mirror row_mask:0xf bank_mask:0xf bound_ctrl:1
	v_add_u32_dpp v70, v96, v88 row_half_mirror row_mask:0xf bank_mask:0xf bound_ctrl:1
	v_add_u32_dpp v71, v97, v89 row_half_mirror row_mask:0xf bank_mask:0xf bound_ctrl:1
	v_add_u32_dpp v72, v98, v90 row_half_mirror row_mask:0xf bank_mask:0xf bound_ctrl:1
	v_add_u32_dpp v73, v99, v91 row_half_mirror row_mask:0xf bank_mask:0xf bound_ctrl:1
	v_add_u32_dpp v74, v100, v92 row_half_mirror row_mask:0xf bank_mask:0xf bound_ctrl:1
	v_add_u32_dpp v75, v101, v93 row_half_mirror row_mask:0xf bank_mask:0xf bound_ctrl:1
	v_cndmask_b32_e64 v94, v70, v68, s[72:73]
	v_cndmask_b32_e64 v95, v71, v69, s[72:73]
	v_cndmask_b32_e64 v96, v74, v72, s[72:73]
	v_cndmask_b32_e64 v97, v75, v73, s[72:73]
	v_cndmask_b32_e64 v86, v68, v70, s[72:73]
	v_cndmask_b32_e64 v87, v69, v71, s[72:73]
	v_cndmask_b32_e64 v88, v72, v74, s[72:73]
	v_cndmask_b32_e64 v89, v73, v75, s[72:73]
	v_add_u32_dpp v68, v94, v86 quad_perm:[1,0,3,2] row_mask:0xf bank_mask:0xf bound_ctrl:1
	v_add_u32_dpp v69, v95, v87 quad_perm:[1,0,3,2] row_mask:0xf bank_mask:0xf bound_ctrl:1
	v_add_u32_dpp v70, v96, v88 quad_perm:[1,0,3,2] row_mask:0xf bank_mask:0xf bound_ctrl:1
	v_add_u32_dpp v71, v97, v89 quad_perm:[1,0,3,2] row_mask:0xf bank_mask:0xf bound_ctrl:1
	v_cndmask_b32_e64 v94, v70, v68, s[74:75]
	v_cndmask_b32_e64 v95, v71, v69, s[74:75]
	v_cndmask_b32_e64 v86, v68, v70, s[74:75]
	v_cndmask_b32_e64 v87, v69, v71, s[74:75]
	v_add_u32_dpp v68, v94, v86 quad_perm:[2,3,0,1] row_mask:0xf bank_mask:0xf bound_ctrl:1
	v_add_u32_dpp v69, v95, v87 quad_perm:[2,3,0,1] row_mask:0xf bank_mask:0xf bound_ctrl:1
	v_cvt_f32_i32_e32 v68, v68
	v_cvt_f32_i32_e32 v69, v69
	s_lshl_b32 s70, s60, 1
	s_add_u32 s70, s70, s28
	s_lshl_b32 s70, s70, 12
	s_add_u32 s70, s70, s68
	v_pk_mul_f32 v[68:69], v[52:53], v[68:69] op_sel_hi:[0,1]
	v_add_u32_e32 v9, s70, v0
	global_store_dwordx2 v9, v[68:69], s[64:65]
	s_mov_b32 s60, s62
	s_cmp_lt_u32 s60, s61
	s_cbranch_scc1 .Lmy_pu0_bodyA

; __device__ __forceinline__ int tid_opaque() { int t = threadIdx.x; asm volatile("" : "+v"(t)); return t; }
; __device__ __forceinline__ void phase_peer_u(const Params& p, int layer, int xs, int wid0, int wstride, char* smraw) {
;   const int tid = tid_opaque(), l = tid & 63, g = l >> 3, j = l & 7;
;   const int wid = wid0 + (tid >> 6);
;   char* xqs = smraw + (tid >> 6) * 256;
;   const int sl = xs >> 1, par = xs & 1;
;   constexpr int TH = T / 2;
;   const unsigned char* Uq = p.Uq + (size_t)(layer * 4 + sl) * NEXP * 128;
;   const unsigned joff = j * 16;
;   u32x4 ni[4];
;   auto load_idx = [&](int tt) {
;     const u32x4* ip = (const u32x4*)((const char*)p.sel_idx + ((unsigned)(2 * tt + par) * 512u + (unsigned)g * 64u));
; #pragma unroll
;     for (int q4 = 0; q4 < 4; ++q4) ni[q4] = ip[q4];
;   };
;   auto issue_rows = [&](int tt, u32x4 (&q)[16], u32x2& xv) {
; #pragma unroll
;     for (int i = 0; i < 16; ++i) q[i] = *(const u32x4*)(Uq + (ni[i >> 2][i & 3] * 128u + joff));
;     xv = *(const u32x2*)((const char*)p.hb + ((unsigned)(2 * tt + par) * 2048u + (unsigned)(sl * 512 + l * 8)));
;   };
;     ...
;   int tt = wid;
;   if (tt < TH) { load_idx(tt); issue_rows(tt, qA, xA); if (tt + wstride < TH) load_idx(tt + wstride); }
.LBB0_1265:
	s_or_b64 exec, exec, s[0:1]
	v_mov_b32_e32 v16, v189
	s_barrier
	s_lshl_b64 s[0:1], s[14:15], 21
	s_waitcnt vmcnt(0)
	v_ashrrev_i32_e32 v80, 6, v16
	v_add_u32_e32 v169, s92, v80
	s_add_u32 s15, s0, 0x800000
	s_movk_i32 s2, 0x4020
	s_addc_u32 s20, s1, 0
	v_cmp_gt_i32_e32 vcc, s2, v169
	s_and_saveexec_b64 s[0:1], vcc
	s_cbranch_execz .LBB0_1284
	v_and_b32_e32 v6, 63, v189
	v_lshrrev_b32_e32 v7, 6, v189
	v_lshlrev_b32_e32 v0, 3, v6
	v_and_b32_e32 v1, 7, v6
	v_and_b32_e32 v9, 4, v6
	v_and_b32_e32 v40, 1, v6
	v_and_b32_e32 v41, 2, v6
	v_cmp_ne_u32_e64 s[12:13], 0, v9
	v_cmp_ne_u32_e64 s[72:73], 0, v40
	v_cmp_ne_u32_e64 s[74:75], 0, v41
	v_lshlrev_b32_e32 v1, 4, v1
	v_lshrrev_b32_e32 v8, 3, v6
	v_readfirstlane_b32 s70, v7
	s_lshl_b32 s71, s28, 9
	v_lshl_add_u32 v2, v8, 6, s71
	v_lshlrev_b32_e32 v5, 6, v8
	v_lshlrev_b32_e32 v3, 8, v7
	v_lshl_add_u32 v4, v1, 1, v3
	v_lshl_add_u32 v3, v6, 2, v3
	s_add_u32 s60, s92, s70
	s_movk_i32 s61, 0x4020
	s_cmp_ge_u32 s60, s61
	s_cbranch_scc1 .Lmy_pu1_done
	s_lshl_b32 s70, s14, 21
	s_add_u32 s70, s70, 0x800000
	s_add_u32 s66, s88, s70
	s_addc_u32 s67, s89, 0
	v_readlane_b32 s64, v254, 4
	v_readlane_b32 s65, v254, 5
	s_lshl_b32 s68, s14, 9
	s_mov_b32 s69, 0x42fe0000
	s_mov_b32 s21, 0xf0f0f0f
	s_mov_b32 s23, 0xf0f0f0f0
	s_lshl_b32 s70, s60, 10
	v_add_u32_e32 v9, s70, v2
	global_load_dwordx4 v[10:13], v9, s[52:53]
	global_load_dwordx4 v[14:17], v9, s[52:53] offset:16
	global_load_dwordx4 v[18:21], v9, s[52:53] offset:32
	global_load_dwordx4 v[22:25], v9, s[52:53] offset:48
	s_waitcnt vmcnt(0)
	v_lshl_add_u32 v6, v10, 7, v1
	global_load_dwordx4 v[106:109], v6, s[66:67]
	v_lshl_add_u32 v7, v11, 7, v1
	global_load_dwordx4 v[110:113], v7, s[66:67]
	v_lshl_add_u32 v6, v12, 7, v1
	global_load_dwordx4 v[114:117], v6, s[66:67]
	v_lshl_add_u32 v7, v13, 7, v1
	global_load_dwordx4 v[118:121], v7, s[66:67]
	v_lshl_add_u32 v6, v14, 7, v1
	global_load_dwordx4 v[122:125], v6, s[66:67]
	v_lshl_add_u32 v7, v15, 7, v1
	global_load_dwordx4 v[126:129], v7, s[66:67]
	v_lshl_add_u32 v6, v16, 7, v1
	global_load_dwordx4 v[130:133], v6, s[66:67]
	v_lshl_add_u32 v7, v17, 7, v1
	global_load_dwordx4 v[134:137], v7, s[66:67]
	v_lshl_add_u32 v6, v18, 7, v1
	global_load_dwordx4 v[138:141], v6, s[66:67]
	v_lshl_add_u32 v7, v19, 7, v1
	global_load_dwordx4 v[142:145], v7, s[66:67]
	v_lshl_add_u32 v6, v20, 7, v1
	global_load_dwordx4 v[146:149], v6, s[66:67]
	v_lshl_add_u32 v7, v21, 7, v1
	global_load_dwordx4 v[150:153], v7, s[66:67]
	v_lshl_add_u32 v6, v22, 7, v1
	global_load_dwordx4 v[154:157], v6, s[66:67]
	v_lshl_add_u32 v7, v23, 7, v1
	global_load_dwordx4 v[158:161], v7, s[66:67]
	v_lshl_add_u32 v6, v24, 7, v1
	global_load_dwordx4 v[162:165], v6, s[66:67]
	v_lshl_add_u32 v7, v25, 7, v1
	global_load_dwordx4 v[166:169], v7, s[66:67]
	s_lshl_b32 s70, s60, 1
	s_add_u32 s70, s70, s28
	s_lshl_b32 s70, s70, 11
	s_add_u32 s70, s70, s68
	v_add_u32_e32 v8, s70, v0
	global_load_dwordx2 v[26:27], v8, s[76:77]
	s_add_u32 s62, s60, s33
	s_cmp_ge_u32 s62, s61
	s_cbranch_scc1 .Lmy_pu1_pro1
	s_lshl_b32 s70, s62, 10
	v_add_u32_e32 v9, s70, v2
	global_load_dwordx4 v[10:13], v9, s[52:53]
	global_load_dwordx4 v[14:17], v9, s[52:53] offset:16
	global_load_dwordx4 v[18:21], v9, s[52:53] offset:32
	global_load_dwordx4 v[22:25], v9, s[52:53] offset:48
